# plus: window carry-over copy split 80/20 between the prologue and the adaLN GEMM phase (was 66/34)
# speedup vs baseline: 1.0059x; 1.0059x over previous
.LBB0_5:
	s_or_b64 exec, exec, s[0:1]
	s_load_dwordx2 s[0:1], s[78:79], 0x2a8
	v_lshl_or_b32 v0, s76, 9, v248
	s_waitcnt lgkmcnt(0)
	s_cmp_lt_i32 s0, 1
	s_cselect_b64 s[10:11], -1, 0
	s_cmp_gt_i32 s1, 0
	s_cselect_b64 s[0:1], -1, 0
	s_and_b64 s[0:1], s[10:11], s[0:1]
	s_andn2_b64 vcc, exec, s[0:1]
	s_cbranch_vccnz .LBB0_232
	s_load_dword s33, s[78:79], 0x2b0
	s_mov_b32 s0, 0x64cccc
	v_lshl_or_b32 v34, s76, 9, v248
	s_waitcnt lgkmcnt(0)
	s_cmp_gt_i32 s33, 56
	s_cselect_b32 s6, s0, 0x7e0000
	v_cmp_le_u32_e32 vcc, s6, v34
	s_and_saveexec_b64 s[0:1], vcc
	s_xor_b64 s[0:1], exec, s[0:1]
	s_cbranch_execz .LBB0_9
	v_lshlrev_b32_e32 v32, 2, v248
	s_or_saveexec_b64 s[0:1], s[0:1]
	s_lshl_b32 s12, s33, 9
	s_xor_b64 exec, exec, s[0:1]
	s_cbranch_execnz .LBB0_10

.LBB0_326:
	s_cmp_lt_i32 s33, 57
	s_cbranch_scc1 .LBB0_345
	v_lshl_or_b32 v1, s76, 9, v248
	v_add_u32_e32 v1, 0x645ccc, v1
	s_mov_b32 s8, 0x7e0000
	v_cmp_gt_u32_e32 vcc, s8, v1
	s_and_saveexec_b64 s[2:3], vcc
	s_cbranch_execz .LBB0_344
	s_lshl_b32 s9, s33, 9
	s_add_i32 s6, s9, 0xffff9000
	s_add_i32 s6, s6, s6
	s_add_i32 s18, s6, s6
	s_lshl_b32 s10, s33, 10
	s_mul_i32 s11, s33, 0x600
	s_lshl_b32 s12, s33, 11
	s_mul_i32 s13, s33, 0xa00
	s_mul_i32 s14, s33, 0xc00
	s_mul_i32 s15, s33, 0xe00
	s_mov_b64 s[4:5], 0
	v_mov_b32_e32 v31, 0
	s_movk_i32 s16, 0x4000
	s_mov_b32 s17, 0x4104105
	s_add_i32 s18, s18, s18
	s_branch .LBB0_330
